# online-softmax rescale only when the block max exceeds the running reference by 2^8 (exact math, stale reference max)
# speedup vs baseline: 1.0209x; 1.0024x over previous
; #define LAS __attribute__((address_space(3)))
; __device__ __forceinline__ float shflx(float v, int mask, int lane) { return __builtin_bit_cast(float, __builtin_amdgcn_ds_bpermute(((lane ^ mask) & 63) << 2, __builtin_bit_cast(int, v))); }
; template <int MODE  > ...
;     ...
;             for (int kk = 0; kk < 4; ++kk) {
;                 const bf16x8 k0 = *(const LAS bf16x8*)(kb + col * KPITCH + kk * 16 + h * 8);
;                 const bf16x8 k1 = *(const LAS bf16x8*)(kb + (32 + col) * KPITCH + kk * 16 + h * 8);
;                 s0 = __builtin_amdgcn_mfma_f32_32x32x16_bf16(k0, qf[kk], s0, 0, 0, 0);
;                 s1 = __builtin_amdgcn_mfma_f32_32x32x16_bf16(k1, qf[kk], s1, 0, 0, 0);
;             }
;             if (MODE != 3) {
;                 float mx = fmaxf(s0[0], s1[0]);
; #pragma unroll
;                 for (int i = 1; i < 16; ++i) mx = fmaxf(mx, fmaxf(s0[i], s1[i]));
;                 mx = fmaxf(mx, shflx(mx, 32, lane));
;                 float alpha = 1.f;
;                 if (__builtin_amdgcn_ballot_w64(fresh || mx > 0.f) != 0ull) {
;                     const float moldr = fresh ? -1e29f : 0.f, mnewr = fmaxf(moldr, mx);
;                     alpha = __builtin_amdgcn_exp2f(moldr - mnewr);
;                     st.m = mest + mnewr;
; #pragma unroll
;                     for (int i = 0; i < 16; ++i) { s0[i] = __builtin_amdgcn_exp2f(s0[i] - mnewr); s1[i] = __builtin_amdgcn_exp2f(s1[i] - mnewr); }
;                     st.o0 *= alpha; st.o1 *= alpha;
.Lm1_qk:
	s_waitcnt lgkmcnt(7)
	v_mfma_f32_32x32x16_bf16 v[50:65], v[66:69], v[144:147], v[50:65]
	s_waitcnt lgkmcnt(6)
	v_mfma_f32_32x32x16_bf16 v[2:17], v[70:73], v[144:147], v[2:17]
	s_waitcnt lgkmcnt(5)
	v_mfma_f32_32x32x16_bf16 v[50:65], v[74:77], v[148:151], v[50:65]
	s_waitcnt lgkmcnt(4)
	v_mfma_f32_32x32x16_bf16 v[2:17], v[78:81], v[148:151], v[2:17]
	s_waitcnt lgkmcnt(3)
	v_mfma_f32_32x32x16_bf16 v[50:65], v[82:85], v[152:155], v[50:65]
	s_waitcnt lgkmcnt(2)
	v_mfma_f32_32x32x16_bf16 v[2:17], v[86:89], v[152:155], v[2:17]
	s_waitcnt lgkmcnt(1)
	v_mfma_f32_32x32x16_bf16 v[50:65], v[90:93], v[156:159], v[50:65]
	s_waitcnt lgkmcnt(0)
	v_mfma_f32_32x32x16_bf16 v[2:17], v[94:97], v[156:159], v[2:17]
	ds_read_b64_tr_b16 v[66:67], v225 offset:18432
	ds_read_b64_tr_b16 v[68:69], v225 offset:19968
	ds_read_b64_tr_b16 v[70:71], v225 offset:18496
	ds_read_b64_tr_b16 v[72:73], v225 offset:20032
	ds_read_b64_tr_b16 v[74:75], v225 offset:21504
	ds_read_b64_tr_b16 v[76:77], v225 offset:23040
	ds_read_b64_tr_b16 v[78:79], v225 offset:21568
	ds_read_b64_tr_b16 v[80:81], v225 offset:23104
	s_nop 3
	v_max3_f32 v234, v50, v51, v52
	v_max3_f32 v234, v234, v53, v54
	v_max3_f32 v234, v234, v55, v56
	v_max3_f32 v234, v234, v57, v58
	v_max3_f32 v234, v234, v59, v60
	v_max3_f32 v234, v234, v61, v62
	v_max3_f32 v234, v234, v63, v64
	v_max3_f32 v235, v2, v3, v4
	v_max3_f32 v235, v235, v5, v6
	v_max3_f32 v235, v235, v7, v8
	v_max3_f32 v235, v235, v9, v10
	v_max3_f32 v235, v235, v11, v12
	v_max3_f32 v235, v235, v13, v14
	v_max3_f32 v235, v235, v15, v16
	v_max3_f32 v234, v234, v65, v17
	v_max_f32_e32 v234, v234, v235
	v_mov_b32_e32 v235, v234
	s_waitcnt lgkmcnt(7)
	ds_read_b64_tr_b16 v[82:83], v225 offset:24576
	ds_read_b64_tr_b16 v[84:85], v225 offset:26112
	ds_read_b64_tr_b16 v[86:87], v225 offset:24640
	ds_read_b64_tr_b16 v[88:89], v225 offset:26176
	ds_read_b64_tr_b16 v[90:91], v225 offset:27648
	ds_read_b64_tr_b16 v[92:93], v225 offset:29184
	ds_read_b64_tr_b16 v[94:95], v225 offset:27712
	ds_read_b64_tr_b16 v[96:97], v225 offset:29248
	v_permlane32_swap_b32_e32 v235, v234
	v_max_f32_e32 v234, v234, v235
	v_cmp_lt_f32_e32 vcc, 0x41000000, v234
	s_or_b64 vcc, s[14:15], vcc
	s_cbranch_vccz .Lm1_norescale
	v_cndmask_b32_e64 v235, 0, v242, s[14:15]
	v_max_f32_e32 v234, v235, v234
	v_sub_f32_e32 v235, v235, v234
	v_exp_f32_e32 v162, v235
	v_add_f32_e32 v194, v1, v234
	v_sub_f32_e32 v114, v50, v234
	v_exp_f32_e32 v114, v114
	v_sub_f32_e32 v98, v2, v234
	v_exp_f32_e32 v98, v98
	v_sub_f32_e32 v115, v51, v234
	v_exp_f32_e32 v115, v115
	v_sub_f32_e32 v99, v3, v234
	v_exp_f32_e32 v99, v99
	v_sub_f32_e32 v116, v52, v234
	v_exp_f32_e32 v116, v116
	v_sub_f32_e32 v100, v4, v234
	v_exp_f32_e32 v100, v100
	v_sub_f32_e32 v117, v53, v234
	v_exp_f32_e32 v117, v117
	v_sub_f32_e32 v101, v5, v234
	v_exp_f32_e32 v101, v101
	v_sub_f32_e32 v118, v54, v234
	v_exp_f32_e32 v118, v118
	v_sub_f32_e32 v102, v6, v234
	v_exp_f32_e32 v102, v102
	v_sub_f32_e32 v119, v55, v234
	v_exp_f32_e32 v119, v119
	v_sub_f32_e32 v103, v7, v234
	v_exp_f32_e32 v103, v103
	v_sub_f32_e32 v120, v56, v234
	v_exp_f32_e32 v120, v120
	v_sub_f32_e32 v104, v8, v234
	v_exp_f32_e32 v104, v104
	v_sub_f32_e32 v121, v57, v234
	v_exp_f32_e32 v121, v121
	v_sub_f32_e32 v105, v9, v234
	v_exp_f32_e32 v105, v105
	v_sub_f32_e32 v122, v58, v234
	v_exp_f32_e32 v122, v122
	v_sub_f32_e32 v106, v10, v234
	v_exp_f32_e32 v106, v106
	v_sub_f32_e32 v123, v59, v234
	v_exp_f32_e32 v123, v123
	v_sub_f32_e32 v107, v11, v234
	v_exp_f32_e32 v107, v107
	v_sub_f32_e32 v124, v60, v234
	v_exp_f32_e32 v124, v124
	v_sub_f32_e32 v108, v12, v234
	v_exp_f32_e32 v108, v108
	v_sub_f32_e32 v125, v61, v234
	v_exp_f32_e32 v125, v125
	v_sub_f32_e32 v109, v13, v234
	v_exp_f32_e32 v109, v109
	v_sub_f32_e32 v126, v62, v234
	v_exp_f32_e32 v126, v126
	v_sub_f32_e32 v110, v14, v234
	v_exp_f32_e32 v110, v110
	v_sub_f32_e32 v127, v63, v234
	v_exp_f32_e32 v127, v127
	v_sub_f32_e32 v111, v15, v234
	v_exp_f32_e32 v111, v111
	v_sub_f32_e32 v128, v64, v234
	v_exp_f32_e32 v128, v128
	v_sub_f32_e32 v112, v16, v234
	v_exp_f32_e32 v112, v112
	v_sub_f32_e32 v129, v65, v234
	v_exp_f32_e32 v129, v129
	v_sub_f32_e32 v113, v17, v234
	v_exp_f32_e32 v113, v113
	v_pk_mul_f32 v[18:19], v[18:19], v[162:163] op_sel_hi:[1,0]
	v_pk_mul_f32 v[20:21], v[20:21], v[162:163] op_sel_hi:[1,0]
	v_pk_mul_f32 v[22:23], v[22:23], v[162:163] op_sel_hi:[1,0]
	v_pk_mul_f32 v[24:25], v[24:25], v[162:163] op_sel_hi:[1,0]
	v_pk_mul_f32 v[26:27], v[26:27], v[162:163] op_sel_hi:[1,0]
	v_pk_mul_f32 v[28:29], v[28:29], v[162:163] op_sel_hi:[1,0]
	v_pk_mul_f32 v[30:31], v[30:31], v[162:163] op_sel_hi:[1,0]
	v_pk_mul_f32 v[32:33], v[32:33], v[162:163] op_sel_hi:[1,0]
	v_pk_mul_f32 v[34:35], v[34:35], v[162:163] op_sel_hi:[1,0]
	v_pk_mul_f32 v[36:37], v[36:37], v[162:163] op_sel_hi:[1,0]
	v_pk_mul_f32 v[38:39], v[38:39], v[162:163] op_sel_hi:[1,0]
	v_pk_mul_f32 v[40:41], v[40:41], v[162:163] op_sel_hi:[1,0]
	v_pk_mul_f32 v[42:43], v[42:43], v[162:163] op_sel_hi:[1,0]
	v_pk_mul_f32 v[44:45], v[44:45], v[162:163] op_sel_hi:[1,0]
	v_pk_mul_f32 v[46:47], v[46:47], v[162:163] op_sel_hi:[1,0]
	v_pk_mul_f32 v[48:49], v[48:49], v[162:163] op_sel_hi:[1,0]
	s_branch .Lm1_pv

; #define LAS __attribute__((address_space(3)))
; __device__ __forceinline__ float shflx(float v, int mask, int lane) { return __builtin_bit_cast(float, __builtin_amdgcn_ds_bpermute(((lane ^ mask) & 63) << 2, __builtin_bit_cast(int, v))); }
; template <int MODE  > ...
;     ...
;             for (int kk = 0; kk < 4; ++kk) {
;                 const bf16x8 k0 = *(const LAS bf16x8*)(kb + col * KPITCH + kk * 16 + h * 8);
;                 const bf16x8 k1 = *(const LAS bf16x8*)(kb + (32 + col) * KPITCH + kk * 16 + h * 8);
;                 s0 = __builtin_amdgcn_mfma_f32_32x32x16_bf16(k0, qf[kk], s0, 0, 0, 0);
;                 s1 = __builtin_amdgcn_mfma_f32_32x32x16_bf16(k1, qf[kk], s1, 0, 0, 0);
;             }
;             if (MODE != 3) {
;                 float mx = fmaxf(s0[0], s1[0]);
; #pragma unroll
;                 for (int i = 1; i < 16; ++i) mx = fmaxf(mx, fmaxf(s0[i], s1[i]));
;                 mx = fmaxf(mx, shflx(mx, 32, lane));
;                 float alpha = 1.f;
;                 if (__builtin_amdgcn_ballot_w64(fresh || mx > 0.f) != 0ull) {
;                     const float moldr = fresh ? -1e29f : 0.f, mnewr = fmaxf(moldr, mx);
;                     alpha = __builtin_amdgcn_exp2f(moldr - mnewr);
;                     st.m = mest + mnewr;
; #pragma unroll
;                     for (int i = 0; i < 16; ++i) { s0[i] = __builtin_amdgcn_exp2f(s0[i] - mnewr); s1[i] = __builtin_amdgcn_exp2f(s1[i] - mnewr); }
;                     st.o0 *= alpha; st.o1 *= alpha;
.Lm2_qk:
	s_waitcnt lgkmcnt(7)
	v_mfma_f32_32x32x16_bf16 v[34:49], v[66:69], v[144:147], v[34:49]
	s_waitcnt lgkmcnt(6)
	v_mfma_f32_32x32x16_bf16 v[50:65], v[70:73], v[144:147], v[50:65]
	s_waitcnt lgkmcnt(5)
	v_mfma_f32_32x32x16_bf16 v[34:49], v[74:77], v[148:151], v[34:49]
	s_waitcnt lgkmcnt(4)
	v_mfma_f32_32x32x16_bf16 v[50:65], v[78:81], v[148:151], v[50:65]
	s_waitcnt lgkmcnt(3)
	v_mfma_f32_32x32x16_bf16 v[34:49], v[82:85], v[152:155], v[34:49]
	s_waitcnt lgkmcnt(2)
	v_mfma_f32_32x32x16_bf16 v[50:65], v[86:89], v[152:155], v[50:65]
	s_waitcnt lgkmcnt(1)
	v_mfma_f32_32x32x16_bf16 v[34:49], v[90:93], v[156:159], v[34:49]
	s_waitcnt lgkmcnt(0)
	v_mfma_f32_32x32x16_bf16 v[50:65], v[94:97], v[156:159], v[50:65]
	ds_read_b64_tr_b16 v[66:67], v225 offset:18432
	ds_read_b64_tr_b16 v[68:69], v225 offset:19968
	ds_read_b64_tr_b16 v[70:71], v225 offset:18496
	ds_read_b64_tr_b16 v[72:73], v225 offset:20032
	ds_read_b64_tr_b16 v[74:75], v225 offset:21504
	ds_read_b64_tr_b16 v[76:77], v225 offset:23040
	ds_read_b64_tr_b16 v[78:79], v225 offset:21568
	ds_read_b64_tr_b16 v[80:81], v225 offset:23104
	s_nop 3
	v_max3_f32 v234, v34, v35, v36
	v_max3_f32 v234, v234, v37, v38
	v_max3_f32 v234, v234, v39, v40
	v_max3_f32 v234, v234, v41, v42
	v_max3_f32 v234, v234, v43, v44
	v_max3_f32 v234, v234, v45, v46
	v_max3_f32 v234, v234, v47, v48
	v_max3_f32 v235, v50, v51, v52
	v_max3_f32 v235, v235, v53, v54
	v_max3_f32 v235, v235, v55, v56
	v_max3_f32 v235, v235, v57, v58
	v_max3_f32 v235, v235, v59, v60
	v_max3_f32 v235, v235, v61, v62
	v_max3_f32 v235, v235, v63, v64
	v_max3_f32 v234, v234, v49, v65
	v_max_f32_e32 v234, v234, v235
	v_mov_b32_e32 v235, v234
	s_waitcnt lgkmcnt(7)
	ds_read_b64_tr_b16 v[82:83], v225 offset:24576
	ds_read_b64_tr_b16 v[84:85], v225 offset:26112
	ds_read_b64_tr_b16 v[86:87], v225 offset:24640
	ds_read_b64_tr_b16 v[88:89], v225 offset:26176
	ds_read_b64_tr_b16 v[90:91], v225 offset:27648
	ds_read_b64_tr_b16 v[92:93], v225 offset:29184
	ds_read_b64_tr_b16 v[94:95], v225 offset:27712
	ds_read_b64_tr_b16 v[96:97], v225 offset:29248
	v_permlane32_swap_b32_e32 v235, v234
	v_max_f32_e32 v234, v234, v235
	v_cmp_lt_f32_e32 vcc, 0x41000000, v234
	s_or_b64 vcc, s[14:15], vcc
	s_cbranch_vccz .Lm2_norescale
	v_cndmask_b32_e64 v235, 0, v242, s[14:15]
	v_max_f32_e32 v234, v235, v234
	v_sub_f32_e32 v235, v235, v234
	v_exp_f32_e32 v160, v235
	v_add_f32_e32 v192, v1, v234
	v_sub_f32_e32 v114, v34, v234
	v_exp_f32_e32 v114, v114
	v_sub_f32_e32 v98, v50, v234
	v_exp_f32_e32 v98, v98
	v_sub_f32_e32 v115, v35, v234
	v_exp_f32_e32 v115, v115
	v_sub_f32_e32 v99, v51, v234
	v_exp_f32_e32 v99, v99
	v_sub_f32_e32 v116, v36, v234
	v_exp_f32_e32 v116, v116
	v_sub_f32_e32 v100, v52, v234
	v_exp_f32_e32 v100, v100
	v_sub_f32_e32 v117, v37, v234
	v_exp_f32_e32 v117, v117
	v_sub_f32_e32 v101, v53, v234
	v_exp_f32_e32 v101, v101
	v_sub_f32_e32 v118, v38, v234
	v_exp_f32_e32 v118, v118
	v_sub_f32_e32 v102, v54, v234
	v_exp_f32_e32 v102, v102
	v_sub_f32_e32 v119, v39, v234
	v_exp_f32_e32 v119, v119
	v_sub_f32_e32 v103, v55, v234
	v_exp_f32_e32 v103, v103
	v_sub_f32_e32 v120, v40, v234
	v_exp_f32_e32 v120, v120
	v_sub_f32_e32 v104, v56, v234
	v_exp_f32_e32 v104, v104
	v_sub_f32_e32 v121, v41, v234
	v_exp_f32_e32 v121, v121
	v_sub_f32_e32 v105, v57, v234
	v_exp_f32_e32 v105, v105
	v_sub_f32_e32 v122, v42, v234
	v_exp_f32_e32 v122, v122
	v_sub_f32_e32 v106, v58, v234
	v_exp_f32_e32 v106, v106
	v_sub_f32_e32 v123, v43, v234
	v_exp_f32_e32 v123, v123
	v_sub_f32_e32 v107, v59, v234
	v_exp_f32_e32 v107, v107
	v_sub_f32_e32 v124, v44, v234
	v_exp_f32_e32 v124, v124
	v_sub_f32_e32 v108, v60, v234
	v_exp_f32_e32 v108, v108
	v_sub_f32_e32 v125, v45, v234
	v_exp_f32_e32 v125, v125
	v_sub_f32_e32 v109, v61, v234
	v_exp_f32_e32 v109, v109
	v_sub_f32_e32 v126, v46, v234
	v_exp_f32_e32 v126, v126
	v_sub_f32_e32 v110, v62, v234
	v_exp_f32_e32 v110, v110
	v_sub_f32_e32 v127, v47, v234
	v_exp_f32_e32 v127, v127
	v_sub_f32_e32 v111, v63, v234
	v_exp_f32_e32 v111, v111
	v_sub_f32_e32 v128, v48, v234
	v_exp_f32_e32 v128, v128
	v_sub_f32_e32 v112, v64, v234
	v_exp_f32_e32 v112, v112
	v_sub_f32_e32 v129, v49, v234
	v_exp_f32_e32 v129, v129
	v_sub_f32_e32 v113, v65, v234
	v_exp_f32_e32 v113, v113
	v_pk_mul_f32 v[18:19], v[18:19], v[160:161] op_sel_hi:[1,0]
	v_pk_mul_f32 v[20:21], v[20:21], v[160:161] op_sel_hi:[1,0]
	v_pk_mul_f32 v[22:23], v[22:23], v[160:161] op_sel_hi:[1,0]
	v_pk_mul_f32 v[24:25], v[24:25], v[160:161] op_sel_hi:[1,0]
	v_pk_mul_f32 v[26:27], v[26:27], v[160:161] op_sel_hi:[1,0]
	v_pk_mul_f32 v[28:29], v[28:29], v[160:161] op_sel_hi:[1,0]
	v_pk_mul_f32 v[30:31], v[30:31], v[160:161] op_sel_hi:[1,0]
	v_pk_mul_f32 v[32:33], v[32:33], v[160:161] op_sel_hi:[1,0]
	v_pk_mul_f32 v[2:3], v[2:3], v[160:161] op_sel_hi:[1,0]
	v_pk_mul_f32 v[4:5], v[4:5], v[160:161] op_sel_hi:[1,0]
	v_pk_mul_f32 v[6:7], v[6:7], v[160:161] op_sel_hi:[1,0]
	v_pk_mul_f32 v[8:9], v[8:9], v[160:161] op_sel_hi:[1,0]
	v_pk_mul_f32 v[10:11], v[10:11], v[160:161] op_sel_hi:[1,0]
	v_pk_mul_f32 v[12:13], v[12:13], v[160:161] op_sel_hi:[1,0]
	v_pk_mul_f32 v[14:15], v[14:15], v[160:161] op_sel_hi:[1,0]
	v_pk_mul_f32 v[16:17], v[16:17], v[160:161] op_sel_hi:[1,0]
	s_branch .Lm2_pv
